# v9 + final RMSNorm g vectors hoisted + write-through (sc1) stores in the residual GEMM epilogues
# speedup vs baseline: 1.0216x; 1.0030x over previous
.LBB0_799:
	v_add_u32_e32 v151, s27, v133
	v_add_u32_e32 v140, s26, v149
	s_mov_b32 s26, 0x8000
	v_add_u32_e32 v142, 0xffff8000, v151
	v_ashrrev_i32_e32 v143, 31, v151
	v_cmp_gt_i32_e32 vcc, s26, v151
	v_readlane_b32 s64, v254, 27
	v_ashrrev_i32_e32 v141, 31, v140
	v_cndmask_b32_e32 v143, 0, v143, vcc
	v_cndmask_b32_e32 v142, v142, v151, vcc
	v_lshlrev_b64 v[144:145], 12, v[142:143]
	v_min_i32_e32 v142, 0x8000, v151
	v_ashrrev_i32_e32 v142, 12, v142
	v_mul_i32_i24_e32 v142, 0x2400, v142
	v_ashrrev_i32_e32 v143, 31, v142
	v_readlane_b32 s65, v254, 28
	v_lshlrev_b64 v[140:141], 2, v[140:141]
	v_mov_b32_e32 v152, s9
	v_lshl_add_u64 v[142:143], v[142:143], 2, s[64:65]
	v_mov_b32_e32 v153, s11
	v_mov_b32_e32 v154, s8
	v_mov_b32_e32 v155, s10
	v_lshl_add_u64 v[168:169], v[142:143], 0, v[140:141]
	s_movk_i32 s27, 0x2000
	v_cndmask_b32_e32 v147, v152, v153, vcc
	v_cndmask_b32_e32 v146, v154, v155, vcc
	v_add_co_u32_e64 v142, s[6:7], s27, v168
	v_lshl_add_u64 v[146:147], v[146:147], 0, v[144:145]
	s_nop 0
	v_addc_co_u32_e64 v143, s[6:7], 0, v169, s[6:7]
	v_lshl_add_u64 v[142:143], v[146:147], 0, v[140:141]
	v_readlane_b32 s48, v251, 19
	v_readlane_b32 s52, v251, 23
	v_readlane_b32 s53, v251, 24
	v_readlane_b32 s54, v251, 25
	v_readlane_b32 s55, v251, 26
	v_readlane_b32 s56, v251, 27
	v_readlane_b32 s57, v251, 28
	v_readlane_b32 s58, v251, 29
	v_readlane_b32 s59, v251, 30
	v_readlane_b32 s60, v251, 31
	v_readlane_b32 s61, v251, 32
	v_readlane_b32 s62, v251, 33
	v_readlane_b32 s63, v251, 34
	s_mov_b64 s[52:53], s[56:57]
	s_mov_b64 s[54:55], s[58:59]
	v_mov_b32_e32 v156, s55
	v_mov_b32_e32 v157, s53
	v_mov_b32_e32 v158, s54
	v_mov_b32_e32 v159, s52
	v_cndmask_b32_e32 v147, v156, v157, vcc
	v_cndmask_b32_e32 v146, v158, v159, vcc
	v_lshl_add_u64 v[144:145], v[146:147], 0, v[144:145]
	v_lshl_add_u64 v[144:145], v[144:145], 0, v[140:141]
	s_mov_b64 s[38:39], 0x2000
	v_lshl_add_u64 v[146:147], v[168:169], 0, s[38:39]
	s_movk_i32 s30, 0x7ff0
	v_cmp_gt_i32_e32 vcc, s30, v151
	s_movk_i32 s31, 0x7fe0
	s_movk_i32 s34, 0x7fd0
	v_readlane_b32 s49, v251, 20
	v_readlane_b32 s50, v251, 21
	v_readlane_b32 s51, v251, 22
	s_mov_b64 s[56:57], s[60:61]
	s_mov_b64 s[58:59], s[62:63]
	v_readlane_b32 s48, v251, 3
	v_readlane_b32 s49, v251, 4
	v_readlane_b32 s50, v251, 5
	v_readlane_b32 s51, v251, 6
	v_readlane_b32 s52, v251, 7
	v_readlane_b32 s53, v251, 8
	v_readlane_b32 s54, v251, 9
	v_readlane_b32 s55, v251, 10
	v_readlane_b32 s56, v251, 11
	v_readlane_b32 s57, v251, 12
	v_readlane_b32 s58, v251, 13
	v_readlane_b32 s59, v251, 14
	v_readlane_b32 s60, v251, 15
	v_readlane_b32 s61, v251, 16
	v_readlane_b32 s62, v251, 17
	v_readlane_b32 s63, v251, 18
	v_readlane_b32 s48, v252, 4
	v_readlane_b32 s49, v252, 5
	v_readlane_b32 s50, v252, 6
	v_readlane_b32 s51, v252, 7
	v_readlane_b32 s52, v252, 8
	v_readlane_b32 s53, v252, 9
	v_readlane_b32 s54, v252, 10
	v_readlane_b32 s55, v252, 11
	v_readlane_b32 s56, v252, 12
	v_readlane_b32 s57, v252, 13
	v_readlane_b32 s58, v252, 14
	v_readlane_b32 s59, v252, 15
	v_readlane_b32 s60, v252, 16
	v_readlane_b32 s61, v252, 17
	v_readlane_b32 s62, v252, 18
	v_readlane_b32 s63, v252, 19
	s_mov_b64 s[94:95], 0x10000
	s_mov_b64 s[96:97], 0x50000
	global_load_dwordx4 v[152:155], v[146:147], off
	global_load_dwordx4 v[156:159], v[146:147], off offset:64
	global_load_dwordx4 v[160:163], v[146:147], off offset:512
	global_load_dwordx4 v[164:167], v[146:147], off offset:576
	v_mov_b64_e32 v[248:249], v[142:143]
	v_mov_b64_e32 v[140:141], v[144:145]
	global_load_dwordx4 v[168:171], v[248:249], off
	global_load_dwordx4 v[172:175], v[248:249], off offset:64
	global_load_dwordx4 v[176:179], v[248:249], off offset:512
	global_load_dwordx4 v[204:207], v[248:249], off offset:576
	v_lshl_add_u64 v[248:249], v[248:249], 0, s[94:95]
	global_load_dwordx4 v[208:211], v[248:249], off
	global_load_dwordx4 v[212:215], v[248:249], off offset:64
	global_load_dwordx4 v[216:219], v[248:249], off offset:512
	global_load_dwordx4 v[220:223], v[248:249], off offset:576
	v_lshl_add_u64 v[248:249], v[248:249], 0, s[94:95]
	global_load_dwordx4 v[224:227], v[248:249], off
	global_load_dwordx4 v[228:231], v[248:249], off offset:64
	global_load_dwordx4 v[232:235], v[248:249], off offset:512
	global_load_dwordx4 v[236:239], v[248:249], off offset:576
	v_lshl_add_u64 v[248:249], v[248:249], 0, s[94:95]
	global_load_dwordx4 v[240:243], v[248:249], off
	global_load_dwordx4 v[244:247], v[248:249], off offset:64
	s_waitcnt vmcnt(13)
	v_pk_mul_f32 v[154:155], v[154:155], 0.5 op_sel_hi:[1,0]
	v_pk_mul_f32 v[152:153], v[152:153], 0.5 op_sel_hi:[1,0]
	v_pk_mul_f32 v[158:159], v[158:159], 0.5 op_sel_hi:[1,0]
	v_pk_mul_f32 v[156:157], v[156:157], 0.5 op_sel_hi:[1,0]
	v_pk_mul_f32 v[162:163], v[162:163], 0.5 op_sel_hi:[1,0]
	v_pk_mul_f32 v[160:161], v[160:161], 0.5 op_sel_hi:[1,0]
	v_pk_mul_f32 v[166:167], v[166:167], 0.5 op_sel_hi:[1,0]
	v_pk_mul_f32 v[164:165], v[164:165], 0.5 op_sel_hi:[1,0]
	v_pk_fma_f32 v[126:127], v[126:127], v[154:155], v[170:171]
	v_pk_fma_f32 v[124:125], v[124:125], v[152:153], v[168:169]
	global_load_dwordx4 v[168:171], v[248:249], off offset:512
	s_waitcnt vmcnt(13)
	v_pk_fma_f32 v[122:123], v[122:123], v[158:159], v[174:175]
	v_pk_fma_f32 v[120:121], v[120:121], v[156:157], v[172:173]
	global_load_dwordx4 v[172:175], v[248:249], off offset:576
	s_waitcnt vmcnt(13)
	v_pk_fma_f32 v[94:95], v[94:95], v[162:163], v[178:179]
	v_pk_fma_f32 v[92:93], v[92:93], v[160:161], v[176:177]
	v_lshl_add_u64 v[248:249], v[248:249], 0, s[96:97]
	global_load_dwordx4 v[176:179], v[248:249], off
	s_waitcnt vmcnt(13)
	v_pk_fma_f32 v[90:91], v[90:91], v[166:167], v[206:207]
	v_pk_fma_f32 v[88:89], v[88:89], v[164:165], v[204:205]
	global_load_dwordx4 v[204:207], v[248:249], off offset:64
	s_waitcnt vmcnt(13)
	v_pk_fma_f32 v[118:119], v[118:119], v[154:155], v[210:211]
	v_pk_fma_f32 v[116:117], v[116:117], v[152:153], v[208:209]
	global_load_dwordx4 v[208:211], v[248:249], off offset:512
	s_waitcnt vmcnt(13)
	v_pk_fma_f32 v[114:115], v[114:115], v[158:159], v[214:215]
	v_pk_fma_f32 v[112:113], v[112:113], v[156:157], v[212:213]
	global_load_dwordx4 v[212:215], v[248:249], off offset:576
	s_waitcnt vmcnt(13)
	v_pk_fma_f32 v[86:87], v[86:87], v[162:163], v[218:219]
	v_pk_fma_f32 v[84:85], v[84:85], v[160:161], v[216:217]
	v_lshl_add_u64 v[248:249], v[248:249], 0, s[94:95]
	global_load_dwordx4 v[216:219], v[248:249], off
	s_waitcnt vmcnt(13)
	v_pk_fma_f32 v[82:83], v[82:83], v[166:167], v[222:223]
	v_pk_fma_f32 v[80:81], v[80:81], v[164:165], v[220:221]
	global_load_dwordx4 v[220:223], v[248:249], off offset:64
	s_waitcnt vmcnt(13)
	v_pk_fma_f32 v[110:111], v[110:111], v[154:155], v[226:227]
	v_pk_fma_f32 v[108:109], v[108:109], v[152:153], v[224:225]
	global_load_dwordx4 v[224:227], v[248:249], off offset:512
	s_waitcnt vmcnt(13)
	v_pk_fma_f32 v[106:107], v[106:107], v[158:159], v[230:231]
	v_pk_fma_f32 v[104:105], v[104:105], v[156:157], v[228:229]
	global_load_dwordx4 v[228:231], v[248:249], off offset:576
	s_waitcnt vmcnt(13)
	v_pk_fma_f32 v[78:79], v[78:79], v[162:163], v[234:235]
	v_pk_fma_f32 v[76:77], v[76:77], v[160:161], v[232:233]
	v_lshl_add_u64 v[248:249], v[248:249], 0, s[94:95]
	global_load_dwordx4 v[232:235], v[248:249], off
	s_waitcnt vmcnt(13)
	v_pk_fma_f32 v[74:75], v[74:75], v[166:167], v[238:239]
	v_pk_fma_f32 v[72:73], v[72:73], v[164:165], v[236:237]
	global_load_dwordx4 v[236:239], v[248:249], off offset:64
	s_waitcnt vmcnt(13)
	v_pk_fma_f32 v[102:103], v[102:103], v[154:155], v[242:243]
	v_pk_fma_f32 v[100:101], v[100:101], v[152:153], v[240:241]
	global_load_dwordx4 v[240:243], v[248:249], off offset:512
	s_waitcnt vmcnt(13)
	v_pk_fma_f32 v[98:99], v[98:99], v[158:159], v[246:247]
	v_pk_fma_f32 v[96:97], v[96:97], v[156:157], v[244:245]
	global_load_dwordx4 v[244:247], v[248:249], off offset:576
	s_waitcnt vmcnt(13)
	v_pk_fma_f32 v[70:71], v[70:71], v[162:163], v[170:171]
	v_pk_fma_f32 v[68:69], v[68:69], v[160:161], v[168:169]
	v_lshl_add_u64 v[248:249], v[248:249], 0, s[94:95]
	global_load_dwordx4 v[168:171], v[248:249], off
	s_waitcnt vmcnt(13)
	v_pk_fma_f32 v[66:67], v[66:67], v[166:167], v[174:175]
	v_pk_fma_f32 v[64:65], v[64:65], v[164:165], v[172:173]
	global_load_dwordx4 v[172:175], v[248:249], off offset:64
	s_waitcnt vmcnt(13)
	v_pk_fma_f32 v[62:63], v[62:63], v[154:155], v[178:179]
	v_pk_fma_f32 v[60:61], v[60:61], v[152:153], v[176:177]
	global_load_dwordx4 v[176:179], v[248:249], off offset:512
	s_waitcnt vmcnt(13)
	v_pk_fma_f32 v[58:59], v[58:59], v[158:159], v[206:207]
	v_pk_fma_f32 v[56:57], v[56:57], v[156:157], v[204:205]
	global_load_dwordx4 v[204:207], v[248:249], off offset:576
	s_waitcnt vmcnt(13)
	v_pk_fma_f32 v[30:31], v[30:31], v[162:163], v[210:211]
	v_pk_fma_f32 v[28:29], v[28:29], v[160:161], v[208:209]
	s_waitcnt vmcnt(12)
	v_pk_fma_f32 v[26:27], v[26:27], v[166:167], v[214:215]
	v_pk_fma_f32 v[24:25], v[24:25], v[164:165], v[212:213]
	s_waitcnt vmcnt(11)
	v_pk_fma_f32 v[54:55], v[54:55], v[154:155], v[218:219]
	v_pk_fma_f32 v[52:53], v[52:53], v[152:153], v[216:217]
	s_waitcnt vmcnt(10)
	v_pk_fma_f32 v[50:51], v[50:51], v[158:159], v[222:223]
	v_pk_fma_f32 v[48:49], v[48:49], v[156:157], v[220:221]
	s_waitcnt vmcnt(9)
	v_pk_fma_f32 v[22:23], v[22:23], v[162:163], v[226:227]
	v_pk_fma_f32 v[20:21], v[20:21], v[160:161], v[224:225]
	s_waitcnt vmcnt(8)
	v_pk_fma_f32 v[18:19], v[18:19], v[166:167], v[230:231]
	v_pk_fma_f32 v[16:17], v[16:17], v[164:165], v[228:229]
	s_waitcnt vmcnt(7)
	v_pk_fma_f32 v[46:47], v[46:47], v[154:155], v[234:235]
	v_pk_fma_f32 v[44:45], v[44:45], v[152:153], v[232:233]
	s_waitcnt vmcnt(6)
	v_pk_fma_f32 v[42:43], v[42:43], v[158:159], v[238:239]
	v_pk_fma_f32 v[40:41], v[40:41], v[156:157], v[236:237]
	s_waitcnt vmcnt(5)
	v_pk_fma_f32 v[14:15], v[14:15], v[162:163], v[242:243]
	v_pk_fma_f32 v[12:13], v[12:13], v[160:161], v[240:241]
	s_waitcnt vmcnt(4)
	v_pk_fma_f32 v[10:11], v[10:11], v[166:167], v[246:247]
	v_pk_fma_f32 v[8:9], v[8:9], v[164:165], v[244:245]
	s_waitcnt vmcnt(3)
	v_pk_fma_f32 v[38:39], v[38:39], v[154:155], v[170:171]
	v_pk_fma_f32 v[36:37], v[36:37], v[152:153], v[168:169]
	s_waitcnt vmcnt(2)
	v_pk_fma_f32 v[34:35], v[34:35], v[158:159], v[174:175]
	v_pk_fma_f32 v[32:33], v[32:33], v[156:157], v[172:173]
	s_waitcnt vmcnt(1)
	v_pk_fma_f32 v[6:7], v[6:7], v[162:163], v[178:179]
	v_pk_fma_f32 v[4:5], v[4:5], v[160:161], v[176:177]
	s_waitcnt vmcnt(0)
	v_pk_fma_f32 v[2:3], v[2:3], v[166:167], v[206:207]
	v_pk_fma_f32 v[0:1], v[0:1], v[164:165], v[204:205]
	global_store_dwordx4 v[140:141], v[124:127], off sc1
	global_store_dwordx4 v[140:141], v[120:123], off offset:64 sc1
	global_store_dwordx4 v[140:141], v[92:95], off offset:512 sc1
	global_store_dwordx4 v[140:141], v[88:91], off offset:576 sc1
	v_lshl_add_u64 v[140:141], v[140:141], 0, s[94:95]
	global_store_dwordx4 v[140:141], v[116:119], off sc1
	global_store_dwordx4 v[140:141], v[112:115], off offset:64 sc1
	global_store_dwordx4 v[140:141], v[84:87], off offset:512 sc1
	global_store_dwordx4 v[140:141], v[80:83], off offset:576 sc1
	v_lshl_add_u64 v[140:141], v[140:141], 0, s[94:95]
	global_store_dwordx4 v[140:141], v[108:111], off sc1
	global_store_dwordx4 v[140:141], v[104:107], off offset:64 sc1
	global_store_dwordx4 v[140:141], v[76:79], off offset:512 sc1
	global_store_dwordx4 v[140:141], v[72:75], off offset:576 sc1
	v_lshl_add_u64 v[140:141], v[140:141], 0, s[94:95]
	global_store_dwordx4 v[140:141], v[100:103], off sc1
	global_store_dwordx4 v[140:141], v[96:99], off offset:64 sc1
	global_store_dwordx4 v[140:141], v[68:71], off offset:512 sc1
	global_store_dwordx4 v[140:141], v[64:67], off offset:576 sc1
	v_lshl_add_u64 v[140:141], v[140:141], 0, s[96:97]
	global_store_dwordx4 v[140:141], v[60:63], off sc1
	global_store_dwordx4 v[140:141], v[56:59], off offset:64 sc1
	global_store_dwordx4 v[140:141], v[28:31], off offset:512 sc1
	global_store_dwordx4 v[140:141], v[24:27], off offset:576 sc1
	v_lshl_add_u64 v[140:141], v[140:141], 0, s[94:95]
	global_store_dwordx4 v[140:141], v[52:55], off sc1
	global_store_dwordx4 v[140:141], v[48:51], off offset:64 sc1
	global_store_dwordx4 v[140:141], v[20:23], off offset:512 sc1
	global_store_dwordx4 v[140:141], v[16:19], off offset:576 sc1
	v_lshl_add_u64 v[140:141], v[140:141], 0, s[94:95]
	global_store_dwordx4 v[140:141], v[44:47], off sc1
	global_store_dwordx4 v[140:141], v[40:43], off offset:64 sc1
	global_store_dwordx4 v[140:141], v[12:15], off offset:512 sc1
	global_store_dwordx4 v[140:141], v[8:11], off offset:576 sc1
	v_lshl_add_u64 v[140:141], v[140:141], 0, s[94:95]
	global_store_dwordx4 v[140:141], v[36:39], off sc1
	global_store_dwordx4 v[140:141], v[32:35], off offset:64 sc1
	global_store_dwordx4 v[140:141], v[4:7], off offset:512 sc1
	global_store_dwordx4 v[140:141], v[0:3], off offset:576 sc1
	s_mov_b32 s26, s28
	s_mov_b32 s27, s29
	s_andn2_b64 vcc, exec, s[14:15]
	s_cbranch_vccz .LBB0_811

.LBB0_1831:
	v_add_u32_e32 v146, s26, v133
	v_min_i32_e32 v144, 0x8000, v146
	v_readlane_b32 s48, v251, 19
	v_ashrrev_i32_e32 v144, 12, v144
	v_readlane_b32 s52, v251, 23
	v_readlane_b32 s53, v251, 24
	v_readlane_b32 s54, v251, 25
	v_readlane_b32 s55, v251, 26
	v_readlane_b32 s56, v251, 27
	v_readlane_b32 s57, v251, 28
	v_readlane_b32 s58, v251, 29
	v_readlane_b32 s59, v251, 30
	v_add_u32_e32 v140, s25, v149
	s_mov_b32 s11, 0x8000
	v_mul_i32_i24_e32 v144, 0x2400, v144
	v_readlane_b32 s60, v251, 31
	v_readlane_b32 s61, v251, 32
	v_readlane_b32 s62, v251, 33
	v_readlane_b32 s63, v251, 34
	s_mov_b64 s[52:53], s[56:57]
	v_readlane_b32 s30, v254, 27
	v_ashrrev_i32_e32 v141, 31, v140
	v_add_u32_e32 v142, 0xffff8000, v146
	v_ashrrev_i32_e32 v143, 31, v146
	v_cmp_gt_i32_e32 vcc, s11, v146
	v_ashrrev_i32_e32 v145, 31, v144
	s_mov_b64 s[54:55], s[58:59]
	v_readlane_b32 s31, v254, 28
	v_cndmask_b32_e32 v143, 0, v143, vcc
	v_cndmask_b32_e32 v142, v142, v146, vcc
	v_mov_b32_e32 v147, s55
	v_mov_b32_e32 v151, s53
	v_mov_b32_e32 v152, s54
	v_mov_b32_e32 v153, s52
	v_lshl_add_u64 v[144:145], v[144:145], 2, s[30:31]
	v_lshlrev_b64 v[140:141], 2, v[140:141]
	v_lshlrev_b64 v[142:143], 12, v[142:143]
	v_cndmask_b32_e32 v155, v147, v151, vcc
	v_cndmask_b32_e32 v154, v152, v153, vcc
	v_lshl_add_u64 v[144:145], v[144:145], 0, v[140:141]
	s_movk_i32 s27, 0x5000
	v_lshl_add_u64 v[142:143], v[154:155], 0, v[142:143]
	v_add_co_u32_e32 v154, vcc, s27, v144
	v_lshl_add_u64 v[142:143], v[142:143], 0, v[140:141]
	s_nop 0
	v_addc_co_u32_e32 v155, vcc, 0, v145, vcc
	s_nop 0
	s_mov_b64 s[28:29], 0x5000
	v_lshl_add_u64 v[144:145], v[144:145], 0, s[28:29]
	s_movk_i32 s13, 0x7ff0
	v_cmp_gt_i32_e32 vcc, s13, v146
	s_movk_i32 s25, 0x7fe0
	s_movk_i32 s26, 0x7fd0
	v_readlane_b32 s49, v251, 20
	v_readlane_b32 s50, v251, 21
	v_readlane_b32 s51, v251, 22
	s_mov_b64 s[56:57], s[60:61]
	s_mov_b64 s[58:59], s[62:63]
	s_mov_b64 s[94:95], 0x10000
	s_mov_b64 s[96:97], 0x50000
	global_load_dwordx4 v[152:155], v[144:145], off
	global_load_dwordx4 v[156:159], v[144:145], off offset:64
	global_load_dwordx4 v[160:163], v[144:145], off offset:512
	global_load_dwordx4 v[164:167], v[144:145], off offset:576
	v_mov_b64_e32 v[248:249], v[142:143]
	v_mov_b64_e32 v[140:141], v[142:143]
	global_load_dwordx4 v[168:171], v[248:249], off
	global_load_dwordx4 v[172:175], v[248:249], off offset:64
	global_load_dwordx4 v[176:179], v[248:249], off offset:512
	global_load_dwordx4 v[204:207], v[248:249], off offset:576
	v_lshl_add_u64 v[248:249], v[248:249], 0, s[94:95]
	global_load_dwordx4 v[208:211], v[248:249], off
	global_load_dwordx4 v[212:215], v[248:249], off offset:64
	global_load_dwordx4 v[216:219], v[248:249], off offset:512
	global_load_dwordx4 v[220:223], v[248:249], off offset:576
	v_lshl_add_u64 v[248:249], v[248:249], 0, s[94:95]
	global_load_dwordx4 v[224:227], v[248:249], off
	global_load_dwordx4 v[228:231], v[248:249], off offset:64
	global_load_dwordx4 v[232:235], v[248:249], off offset:512
	global_load_dwordx4 v[236:239], v[248:249], off offset:576
	v_lshl_add_u64 v[248:249], v[248:249], 0, s[94:95]
	global_load_dwordx4 v[240:243], v[248:249], off
	global_load_dwordx4 v[244:247], v[248:249], off offset:64
	s_waitcnt vmcnt(13)
	v_pk_fma_f32 v[126:127], v[126:127], v[154:155], v[170:171]
	v_pk_fma_f32 v[124:125], v[124:125], v[152:153], v[168:169]
	global_load_dwordx4 v[168:171], v[248:249], off offset:512
	s_waitcnt vmcnt(13)
	v_pk_fma_f32 v[122:123], v[122:123], v[158:159], v[174:175]
	v_pk_fma_f32 v[120:121], v[120:121], v[156:157], v[172:173]
	global_load_dwordx4 v[172:175], v[248:249], off offset:576
	s_waitcnt vmcnt(13)
	v_pk_fma_f32 v[94:95], v[94:95], v[162:163], v[178:179]
	v_pk_fma_f32 v[92:93], v[92:93], v[160:161], v[176:177]
	v_lshl_add_u64 v[248:249], v[248:249], 0, s[96:97]
	global_load_dwordx4 v[176:179], v[248:249], off
	s_waitcnt vmcnt(13)
	v_pk_fma_f32 v[90:91], v[90:91], v[166:167], v[206:207]
	v_pk_fma_f32 v[88:89], v[88:89], v[164:165], v[204:205]
	global_load_dwordx4 v[204:207], v[248:249], off offset:64
	s_waitcnt vmcnt(13)
	v_pk_fma_f32 v[118:119], v[118:119], v[154:155], v[210:211]
	v_pk_fma_f32 v[116:117], v[116:117], v[152:153], v[208:209]
	global_load_dwordx4 v[208:211], v[248:249], off offset:512
	s_waitcnt vmcnt(13)
	v_pk_fma_f32 v[114:115], v[114:115], v[158:159], v[214:215]
	v_pk_fma_f32 v[112:113], v[112:113], v[156:157], v[212:213]
	global_load_dwordx4 v[212:215], v[248:249], off offset:576
	s_waitcnt vmcnt(13)
	v_pk_fma_f32 v[86:87], v[86:87], v[162:163], v[218:219]
	v_pk_fma_f32 v[84:85], v[84:85], v[160:161], v[216:217]
	v_lshl_add_u64 v[248:249], v[248:249], 0, s[94:95]
	global_load_dwordx4 v[216:219], v[248:249], off
	s_waitcnt vmcnt(13)
	v_pk_fma_f32 v[82:83], v[82:83], v[166:167], v[222:223]
	v_pk_fma_f32 v[80:81], v[80:81], v[164:165], v[220:221]
	global_load_dwordx4 v[220:223], v[248:249], off offset:64
	s_waitcnt vmcnt(13)
	v_pk_fma_f32 v[110:111], v[110:111], v[154:155], v[226:227]
	v_pk_fma_f32 v[108:109], v[108:109], v[152:153], v[224:225]
	global_load_dwordx4 v[224:227], v[248:249], off offset:512
	s_waitcnt vmcnt(13)
	v_pk_fma_f32 v[106:107], v[106:107], v[158:159], v[230:231]
	v_pk_fma_f32 v[104:105], v[104:105], v[156:157], v[228:229]
	global_load_dwordx4 v[228:231], v[248:249], off offset:576
	s_waitcnt vmcnt(13)
	v_pk_fma_f32 v[78:79], v[78:79], v[162:163], v[234:235]
	v_pk_fma_f32 v[76:77], v[76:77], v[160:161], v[232:233]
	v_lshl_add_u64 v[248:249], v[248:249], 0, s[94:95]
	global_load_dwordx4 v[232:235], v[248:249], off
	s_waitcnt vmcnt(13)
	v_pk_fma_f32 v[74:75], v[74:75], v[166:167], v[238:239]
	v_pk_fma_f32 v[72:73], v[72:73], v[164:165], v[236:237]
	global_load_dwordx4 v[236:239], v[248:249], off offset:64
	s_waitcnt vmcnt(13)
	v_pk_fma_f32 v[102:103], v[102:103], v[154:155], v[242:243]
	v_pk_fma_f32 v[100:101], v[100:101], v[152:153], v[240:241]
	global_load_dwordx4 v[240:243], v[248:249], off offset:512
	s_waitcnt vmcnt(13)
	v_pk_fma_f32 v[98:99], v[98:99], v[158:159], v[246:247]
	v_pk_fma_f32 v[96:97], v[96:97], v[156:157], v[244:245]
	global_load_dwordx4 v[244:247], v[248:249], off offset:576
	s_waitcnt vmcnt(13)
	v_pk_fma_f32 v[70:71], v[70:71], v[162:163], v[170:171]
	v_pk_fma_f32 v[68:69], v[68:69], v[160:161], v[168:169]
	v_lshl_add_u64 v[248:249], v[248:249], 0, s[94:95]
	global_load_dwordx4 v[168:171], v[248:249], off
	s_waitcnt vmcnt(13)
	v_pk_fma_f32 v[66:67], v[66:67], v[166:167], v[174:175]
	v_pk_fma_f32 v[64:65], v[64:65], v[164:165], v[172:173]
	global_load_dwordx4 v[172:175], v[248:249], off offset:64
	s_waitcnt vmcnt(13)
	v_pk_fma_f32 v[62:63], v[62:63], v[154:155], v[178:179]
	v_pk_fma_f32 v[60:61], v[60:61], v[152:153], v[176:177]
	global_load_dwordx4 v[176:179], v[248:249], off offset:512
	s_waitcnt vmcnt(13)
	v_pk_fma_f32 v[58:59], v[58:59], v[158:159], v[206:207]
	v_pk_fma_f32 v[56:57], v[56:57], v[156:157], v[204:205]
	global_load_dwordx4 v[204:207], v[248:249], off offset:576
	s_waitcnt vmcnt(13)
	v_pk_fma_f32 v[30:31], v[30:31], v[162:163], v[210:211]
	v_pk_fma_f32 v[28:29], v[28:29], v[160:161], v[208:209]
	s_waitcnt vmcnt(12)
	v_pk_fma_f32 v[26:27], v[26:27], v[166:167], v[214:215]
	v_pk_fma_f32 v[24:25], v[24:25], v[164:165], v[212:213]
	s_waitcnt vmcnt(11)
	v_pk_fma_f32 v[54:55], v[54:55], v[154:155], v[218:219]
	v_pk_fma_f32 v[52:53], v[52:53], v[152:153], v[216:217]
	s_waitcnt vmcnt(10)
	v_pk_fma_f32 v[50:51], v[50:51], v[158:159], v[222:223]
	v_pk_fma_f32 v[48:49], v[48:49], v[156:157], v[220:221]
	s_waitcnt vmcnt(9)
	v_pk_fma_f32 v[22:23], v[22:23], v[162:163], v[226:227]
	v_pk_fma_f32 v[20:21], v[20:21], v[160:161], v[224:225]
	s_waitcnt vmcnt(8)
	v_pk_fma_f32 v[18:19], v[18:19], v[166:167], v[230:231]
	v_pk_fma_f32 v[16:17], v[16:17], v[164:165], v[228:229]
	s_waitcnt vmcnt(7)
	v_pk_fma_f32 v[46:47], v[46:47], v[154:155], v[234:235]
	v_pk_fma_f32 v[44:45], v[44:45], v[152:153], v[232:233]
	s_waitcnt vmcnt(6)
	v_pk_fma_f32 v[42:43], v[42:43], v[158:159], v[238:239]
	v_pk_fma_f32 v[40:41], v[40:41], v[156:157], v[236:237]
	s_waitcnt vmcnt(5)
	v_pk_fma_f32 v[14:15], v[14:15], v[162:163], v[242:243]
	v_pk_fma_f32 v[12:13], v[12:13], v[160:161], v[240:241]
	s_waitcnt vmcnt(4)
	v_pk_fma_f32 v[10:11], v[10:11], v[166:167], v[246:247]
	v_pk_fma_f32 v[8:9], v[8:9], v[164:165], v[244:245]
	s_waitcnt vmcnt(3)
	v_pk_fma_f32 v[38:39], v[38:39], v[154:155], v[170:171]
	v_pk_fma_f32 v[36:37], v[36:37], v[152:153], v[168:169]
	s_waitcnt vmcnt(2)
	v_pk_fma_f32 v[34:35], v[34:35], v[158:159], v[174:175]
	v_pk_fma_f32 v[32:33], v[32:33], v[156:157], v[172:173]
	s_waitcnt vmcnt(1)
	v_pk_fma_f32 v[6:7], v[6:7], v[162:163], v[178:179]
	v_pk_fma_f32 v[4:5], v[4:5], v[160:161], v[176:177]
	s_waitcnt vmcnt(0)
	v_pk_fma_f32 v[2:3], v[2:3], v[166:167], v[206:207]
	v_pk_fma_f32 v[0:1], v[0:1], v[164:165], v[204:205]
	global_store_dwordx4 v[140:141], v[124:127], off sc1
	global_store_dwordx4 v[140:141], v[120:123], off offset:64 sc1
	global_store_dwordx4 v[140:141], v[92:95], off offset:512 sc1
	global_store_dwordx4 v[140:141], v[88:91], off offset:576 sc1
	v_lshl_add_u64 v[140:141], v[140:141], 0, s[94:95]
	global_store_dwordx4 v[140:141], v[116:119], off sc1
	global_store_dwordx4 v[140:141], v[112:115], off offset:64 sc1
	global_store_dwordx4 v[140:141], v[84:87], off offset:512 sc1
	global_store_dwordx4 v[140:141], v[80:83], off offset:576 sc1
	v_lshl_add_u64 v[140:141], v[140:141], 0, s[94:95]
	global_store_dwordx4 v[140:141], v[108:111], off sc1
	global_store_dwordx4 v[140:141], v[104:107], off offset:64 sc1
	global_store_dwordx4 v[140:141], v[76:79], off offset:512 sc1
	global_store_dwordx4 v[140:141], v[72:75], off offset:576 sc1
	v_lshl_add_u64 v[140:141], v[140:141], 0, s[94:95]
	global_store_dwordx4 v[140:141], v[100:103], off sc1
	global_store_dwordx4 v[140:141], v[96:99], off offset:64 sc1
	global_store_dwordx4 v[140:141], v[68:71], off offset:512 sc1
	global_store_dwordx4 v[140:141], v[64:67], off offset:576 sc1
	v_lshl_add_u64 v[140:141], v[140:141], 0, s[96:97]
	global_store_dwordx4 v[140:141], v[60:63], off sc1
	global_store_dwordx4 v[140:141], v[56:59], off offset:64 sc1
	global_store_dwordx4 v[140:141], v[28:31], off offset:512 sc1
	global_store_dwordx4 v[140:141], v[24:27], off offset:576 sc1
	v_lshl_add_u64 v[140:141], v[140:141], 0, s[94:95]
	global_store_dwordx4 v[140:141], v[52:55], off sc1
	global_store_dwordx4 v[140:141], v[48:51], off offset:64 sc1
	global_store_dwordx4 v[140:141], v[20:23], off offset:512 sc1
	global_store_dwordx4 v[140:141], v[16:19], off offset:576 sc1
	v_lshl_add_u64 v[140:141], v[140:141], 0, s[94:95]
	global_store_dwordx4 v[140:141], v[44:47], off sc1
	global_store_dwordx4 v[140:141], v[40:43], off offset:64 sc1
	global_store_dwordx4 v[140:141], v[12:15], off offset:512 sc1
	global_store_dwordx4 v[140:141], v[8:11], off offset:576 sc1
	v_lshl_add_u64 v[140:141], v[140:141], 0, s[94:95]
	global_store_dwordx4 v[140:141], v[36:39], off sc1
	global_store_dwordx4 v[140:141], v[32:35], off offset:64 sc1
	global_store_dwordx4 v[140:141], v[4:7], off offset:512 sc1
	global_store_dwordx4 v[140:141], v[0:3], off offset:576 sc1
	s_mov_b32 s25, s10
	s_mov_b32 s26, s12
	s_andn2_b64 vcc, exec, s[8:9]
	s_cbranch_vccz .LBB0_1843

.LBB0_2026:
	v_add_u32_e32 v146, s25, v133
	v_min_i32_e32 v144, 0x8000, v146
	v_readlane_b32 s48, v251, 19
	v_ashrrev_i32_e32 v144, 12, v144
	v_readlane_b32 s52, v251, 23
	v_readlane_b32 s53, v251, 24
	v_readlane_b32 s54, v251, 25
	v_readlane_b32 s55, v251, 26
	v_readlane_b32 s56, v251, 27
	v_readlane_b32 s57, v251, 28
	v_readlane_b32 s58, v251, 29
	v_readlane_b32 s59, v251, 30
	v_add_u32_e32 v140, s24, v149
	s_mov_b32 s24, 0x8000
	v_mul_i32_i24_e32 v144, 0x2400, v144
	v_readlane_b32 s60, v251, 31
	v_readlane_b32 s61, v251, 32
	v_readlane_b32 s62, v251, 33
	v_readlane_b32 s63, v251, 34
	s_mov_b64 s[52:53], s[56:57]
	v_readlane_b32 s30, v254, 27
	v_ashrrev_i32_e32 v141, 31, v140
	v_add_u32_e32 v142, 0xffff8000, v146
	v_ashrrev_i32_e32 v143, 31, v146
	v_cmp_gt_i32_e32 vcc, s24, v146
	v_ashrrev_i32_e32 v145, 31, v144
	s_mov_b64 s[54:55], s[58:59]
	v_readlane_b32 s31, v254, 28
	v_cndmask_b32_e32 v143, 0, v143, vcc
	v_cndmask_b32_e32 v142, v142, v146, vcc
	v_mov_b32_e32 v147, s55
	v_mov_b32_e32 v151, s53
	v_mov_b32_e32 v152, s54
	v_mov_b32_e32 v153, s52
	v_lshl_add_u64 v[144:145], v[144:145], 2, s[30:31]
	v_lshlrev_b64 v[140:141], 2, v[140:141]
	v_lshlrev_b64 v[142:143], 12, v[142:143]
	v_cndmask_b32_e32 v155, v147, v151, vcc
	v_cndmask_b32_e32 v154, v152, v153, vcc
	v_lshl_add_u64 v[144:145], v[144:145], 0, v[140:141]
	v_lshl_add_u64 v[142:143], v[154:155], 0, v[142:143]
	v_add_co_u32_e32 v154, vcc, s24, v144
	v_lshl_add_u64 v[142:143], v[142:143], 0, v[140:141]
	s_nop 0
	v_addc_co_u32_e32 v155, vcc, 0, v145, vcc
	s_mov_b64 s[28:29], 0x8000
	v_lshl_add_u64 v[144:145], v[144:145], 0, s[28:29]
	s_movk_i32 s25, 0x7ff0
	v_cmp_gt_i32_e32 vcc, s25, v146
	s_movk_i32 s26, 0x7fe0
	s_movk_i32 s27, 0x7fd0
	v_readlane_b32 s49, v251, 20
	v_readlane_b32 s50, v251, 21
	v_readlane_b32 s51, v251, 22
	s_mov_b64 s[56:57], s[60:61]
	s_mov_b64 s[58:59], s[62:63]
	v_readlane_b32 s48, v251, 3
	v_readlane_b32 s49, v251, 4
	v_readlane_b32 s52, v251, 7
	v_readlane_b32 s53, v251, 8
	v_readlane_b32 s60, v251, 15
	v_readlane_b32 s61, v251, 16
	v_readlane_b32 s50, v251, 5
	v_readlane_b32 s51, v251, 6
	v_readlane_b32 s54, v251, 9
	v_readlane_b32 s55, v251, 10
	v_readlane_b32 s56, v251, 11
	v_readlane_b32 s57, v251, 12
	v_readlane_b32 s58, v251, 13
	v_readlane_b32 s59, v251, 14
	v_readlane_b32 s62, v251, 17
	v_readlane_b32 s63, v251, 18
	s_mov_b64 s[94:95], 0x10000
	s_mov_b64 s[96:97], 0x50000
	global_load_dwordx4 v[152:155], v[144:145], off
	global_load_dwordx4 v[156:159], v[144:145], off offset:64
	global_load_dwordx4 v[160:163], v[144:145], off offset:512
	global_load_dwordx4 v[164:167], v[144:145], off offset:576
	v_mov_b64_e32 v[248:249], v[142:143]
	v_mov_b64_e32 v[140:141], v[142:143]
	global_load_dwordx4 v[168:171], v[248:249], off
	global_load_dwordx4 v[172:175], v[248:249], off offset:64
	global_load_dwordx4 v[176:179], v[248:249], off offset:512
	global_load_dwordx4 v[204:207], v[248:249], off offset:576
	v_lshl_add_u64 v[248:249], v[248:249], 0, s[94:95]
	global_load_dwordx4 v[208:211], v[248:249], off
	global_load_dwordx4 v[212:215], v[248:249], off offset:64
	global_load_dwordx4 v[216:219], v[248:249], off offset:512
	global_load_dwordx4 v[220:223], v[248:249], off offset:576
	v_lshl_add_u64 v[248:249], v[248:249], 0, s[94:95]
	global_load_dwordx4 v[224:227], v[248:249], off
	global_load_dwordx4 v[228:231], v[248:249], off offset:64
	global_load_dwordx4 v[232:235], v[248:249], off offset:512
	global_load_dwordx4 v[236:239], v[248:249], off offset:576
	v_lshl_add_u64 v[248:249], v[248:249], 0, s[94:95]
	global_load_dwordx4 v[240:243], v[248:249], off
	global_load_dwordx4 v[244:247], v[248:249], off offset:64
	s_waitcnt vmcnt(13)
	v_pk_mul_f32 v[154:155], v[154:155], 0.5 op_sel_hi:[1,0]
	v_pk_mul_f32 v[152:153], v[152:153], 0.5 op_sel_hi:[1,0]
	v_pk_mul_f32 v[158:159], v[158:159], 0.5 op_sel_hi:[1,0]
	v_pk_mul_f32 v[156:157], v[156:157], 0.5 op_sel_hi:[1,0]
	v_pk_mul_f32 v[162:163], v[162:163], 0.5 op_sel_hi:[1,0]
	v_pk_mul_f32 v[160:161], v[160:161], 0.5 op_sel_hi:[1,0]
	v_pk_mul_f32 v[166:167], v[166:167], 0.5 op_sel_hi:[1,0]
	v_pk_mul_f32 v[164:165], v[164:165], 0.5 op_sel_hi:[1,0]
	v_pk_fma_f32 v[126:127], v[126:127], v[154:155], v[170:171]
	v_pk_fma_f32 v[124:125], v[124:125], v[152:153], v[168:169]
	global_load_dwordx4 v[168:171], v[248:249], off offset:512
	s_waitcnt vmcnt(13)
	v_pk_fma_f32 v[122:123], v[122:123], v[158:159], v[174:175]
	v_pk_fma_f32 v[120:121], v[120:121], v[156:157], v[172:173]
	global_load_dwordx4 v[172:175], v[248:249], off offset:576
	s_waitcnt vmcnt(13)
	v_pk_fma_f32 v[98:99], v[98:99], v[162:163], v[178:179]
	v_pk_fma_f32 v[96:97], v[96:97], v[160:161], v[176:177]
	v_lshl_add_u64 v[248:249], v[248:249], 0, s[96:97]
	global_load_dwordx4 v[176:179], v[248:249], off
	s_waitcnt vmcnt(13)
	v_pk_fma_f32 v[90:91], v[90:91], v[166:167], v[206:207]
	v_pk_fma_f32 v[88:89], v[88:89], v[164:165], v[204:205]
	global_load_dwordx4 v[204:207], v[248:249], off offset:64
	s_waitcnt vmcnt(13)
	v_pk_fma_f32 v[118:119], v[118:119], v[154:155], v[210:211]
	v_pk_fma_f32 v[116:117], v[116:117], v[152:153], v[208:209]
	global_load_dwordx4 v[208:211], v[248:249], off offset:512
	s_waitcnt vmcnt(13)
	v_pk_fma_f32 v[114:115], v[114:115], v[158:159], v[214:215]
	v_pk_fma_f32 v[112:113], v[112:113], v[156:157], v[212:213]
	global_load_dwordx4 v[212:215], v[248:249], off offset:576
	s_waitcnt vmcnt(13)
	v_pk_fma_f32 v[86:87], v[86:87], v[162:163], v[218:219]
	v_pk_fma_f32 v[84:85], v[84:85], v[160:161], v[216:217]
	v_lshl_add_u64 v[248:249], v[248:249], 0, s[94:95]
	global_load_dwordx4 v[216:219], v[248:249], off
	s_waitcnt vmcnt(13)
	v_pk_fma_f32 v[82:83], v[82:83], v[166:167], v[222:223]
	v_pk_fma_f32 v[80:81], v[80:81], v[164:165], v[220:221]
	global_load_dwordx4 v[220:223], v[248:249], off offset:64
	s_waitcnt vmcnt(13)
	v_pk_fma_f32 v[110:111], v[110:111], v[154:155], v[226:227]
	v_pk_fma_f32 v[108:109], v[108:109], v[152:153], v[224:225]
	global_load_dwordx4 v[224:227], v[248:249], off offset:512
	s_waitcnt vmcnt(13)
	v_pk_fma_f32 v[106:107], v[106:107], v[158:159], v[230:231]
	v_pk_fma_f32 v[104:105], v[104:105], v[156:157], v[228:229]
	global_load_dwordx4 v[228:231], v[248:249], off offset:576
	s_waitcnt vmcnt(13)
	v_pk_fma_f32 v[78:79], v[78:79], v[162:163], v[234:235]
	v_pk_fma_f32 v[76:77], v[76:77], v[160:161], v[232:233]
	v_lshl_add_u64 v[248:249], v[248:249], 0, s[94:95]
	global_load_dwordx4 v[232:235], v[248:249], off
	s_waitcnt vmcnt(13)
	v_pk_fma_f32 v[74:75], v[74:75], v[166:167], v[238:239]
	v_pk_fma_f32 v[72:73], v[72:73], v[164:165], v[236:237]
	global_load_dwordx4 v[236:239], v[248:249], off offset:64
	s_waitcnt vmcnt(13)
	v_pk_fma_f32 v[102:103], v[102:103], v[154:155], v[242:243]
	v_pk_fma_f32 v[100:101], v[100:101], v[152:153], v[240:241]
	global_load_dwordx4 v[240:243], v[248:249], off offset:512
	s_waitcnt vmcnt(13)
	v_pk_fma_f32 v[94:95], v[94:95], v[158:159], v[246:247]
	v_pk_fma_f32 v[92:93], v[92:93], v[156:157], v[244:245]
	global_load_dwordx4 v[244:247], v[248:249], off offset:576
	s_waitcnt vmcnt(13)
	v_pk_fma_f32 v[70:71], v[70:71], v[162:163], v[170:171]
	v_pk_fma_f32 v[68:69], v[68:69], v[160:161], v[168:169]
	v_lshl_add_u64 v[248:249], v[248:249], 0, s[94:95]
	global_load_dwordx4 v[168:171], v[248:249], off
	s_waitcnt vmcnt(13)
	v_pk_fma_f32 v[62:63], v[62:63], v[166:167], v[174:175]
	v_pk_fma_f32 v[60:61], v[60:61], v[164:165], v[172:173]
	global_load_dwordx4 v[172:175], v[248:249], off offset:64
	s_waitcnt vmcnt(13)
	v_pk_fma_f32 v[66:67], v[66:67], v[154:155], v[178:179]
	v_pk_fma_f32 v[64:65], v[64:65], v[152:153], v[176:177]
	global_load_dwordx4 v[176:179], v[248:249], off offset:512
	s_waitcnt vmcnt(13)
	v_pk_fma_f32 v[58:59], v[58:59], v[158:159], v[206:207]
	v_pk_fma_f32 v[56:57], v[56:57], v[156:157], v[204:205]
	global_load_dwordx4 v[204:207], v[248:249], off offset:576
	s_waitcnt vmcnt(13)
	v_pk_fma_f32 v[30:31], v[30:31], v[162:163], v[210:211]
	v_pk_fma_f32 v[28:29], v[28:29], v[160:161], v[208:209]
	s_waitcnt vmcnt(12)
	v_pk_fma_f32 v[26:27], v[26:27], v[166:167], v[214:215]
	v_pk_fma_f32 v[24:25], v[24:25], v[164:165], v[212:213]
	s_waitcnt vmcnt(11)
	v_pk_fma_f32 v[54:55], v[54:55], v[154:155], v[218:219]
	v_pk_fma_f32 v[52:53], v[52:53], v[152:153], v[216:217]
	s_waitcnt vmcnt(10)
	v_pk_fma_f32 v[50:51], v[50:51], v[158:159], v[222:223]
	v_pk_fma_f32 v[48:49], v[48:49], v[156:157], v[220:221]
	s_waitcnt vmcnt(9)
	v_pk_fma_f32 v[22:23], v[22:23], v[162:163], v[226:227]
	v_pk_fma_f32 v[20:21], v[20:21], v[160:161], v[224:225]
	s_waitcnt vmcnt(8)
	v_pk_fma_f32 v[18:19], v[18:19], v[166:167], v[230:231]
	v_pk_fma_f32 v[16:17], v[16:17], v[164:165], v[228:229]
	s_waitcnt vmcnt(7)
	v_pk_fma_f32 v[46:47], v[46:47], v[154:155], v[234:235]
	v_pk_fma_f32 v[44:45], v[44:45], v[152:153], v[232:233]
	s_waitcnt vmcnt(6)
	v_pk_fma_f32 v[42:43], v[42:43], v[158:159], v[238:239]
	v_pk_fma_f32 v[40:41], v[40:41], v[156:157], v[236:237]
	s_waitcnt vmcnt(5)
	v_pk_fma_f32 v[14:15], v[14:15], v[162:163], v[242:243]
	v_pk_fma_f32 v[12:13], v[12:13], v[160:161], v[240:241]
	s_waitcnt vmcnt(4)
	v_pk_fma_f32 v[10:11], v[10:11], v[166:167], v[246:247]
	v_pk_fma_f32 v[8:9], v[8:9], v[164:165], v[244:245]
	s_waitcnt vmcnt(3)
	v_pk_fma_f32 v[38:39], v[38:39], v[154:155], v[170:171]
	v_pk_fma_f32 v[36:37], v[36:37], v[152:153], v[168:169]
	s_waitcnt vmcnt(2)
	v_pk_fma_f32 v[34:35], v[34:35], v[158:159], v[174:175]
	v_pk_fma_f32 v[32:33], v[32:33], v[156:157], v[172:173]
	s_waitcnt vmcnt(1)
	v_pk_fma_f32 v[6:7], v[6:7], v[162:163], v[178:179]
	v_pk_fma_f32 v[4:5], v[4:5], v[160:161], v[176:177]
	s_waitcnt vmcnt(0)
	v_pk_fma_f32 v[2:3], v[2:3], v[166:167], v[206:207]
	v_pk_fma_f32 v[0:1], v[0:1], v[164:165], v[204:205]
	global_store_dwordx4 v[140:141], v[124:127], off sc1
	global_store_dwordx4 v[140:141], v[120:123], off offset:64 sc1
	global_store_dwordx4 v[140:141], v[96:99], off offset:512 sc1
	global_store_dwordx4 v[140:141], v[88:91], off offset:576 sc1
	v_lshl_add_u64 v[140:141], v[140:141], 0, s[94:95]
	global_store_dwordx4 v[140:141], v[116:119], off sc1
	global_store_dwordx4 v[140:141], v[112:115], off offset:64 sc1
	global_store_dwordx4 v[140:141], v[84:87], off offset:512 sc1
	global_store_dwordx4 v[140:141], v[80:83], off offset:576 sc1
	v_lshl_add_u64 v[140:141], v[140:141], 0, s[94:95]
	global_store_dwordx4 v[140:141], v[108:111], off sc1
	global_store_dwordx4 v[140:141], v[104:107], off offset:64 sc1
	global_store_dwordx4 v[140:141], v[76:79], off offset:512 sc1
	global_store_dwordx4 v[140:141], v[72:75], off offset:576 sc1
	v_lshl_add_u64 v[140:141], v[140:141], 0, s[94:95]
	global_store_dwordx4 v[140:141], v[100:103], off sc1
	global_store_dwordx4 v[140:141], v[92:95], off offset:64 sc1
	global_store_dwordx4 v[140:141], v[68:71], off offset:512 sc1
	global_store_dwordx4 v[140:141], v[60:63], off offset:576 sc1
	v_lshl_add_u64 v[140:141], v[140:141], 0, s[96:97]
	global_store_dwordx4 v[140:141], v[64:67], off sc1
	global_store_dwordx4 v[140:141], v[56:59], off offset:64 sc1
	global_store_dwordx4 v[140:141], v[28:31], off offset:512 sc1
	global_store_dwordx4 v[140:141], v[24:27], off offset:576 sc1
	v_lshl_add_u64 v[140:141], v[140:141], 0, s[94:95]
	global_store_dwordx4 v[140:141], v[52:55], off sc1
	global_store_dwordx4 v[140:141], v[48:51], off offset:64 sc1
	global_store_dwordx4 v[140:141], v[20:23], off offset:512 sc1
	global_store_dwordx4 v[140:141], v[16:19], off offset:576 sc1
	v_lshl_add_u64 v[140:141], v[140:141], 0, s[94:95]
	global_store_dwordx4 v[140:141], v[44:47], off sc1
	global_store_dwordx4 v[140:141], v[40:43], off offset:64 sc1
	global_store_dwordx4 v[140:141], v[12:15], off offset:512 sc1
	global_store_dwordx4 v[140:141], v[8:11], off offset:576 sc1
	v_lshl_add_u64 v[140:141], v[140:141], 0, s[94:95]
	global_store_dwordx4 v[140:141], v[36:39], off sc1
	global_store_dwordx4 v[140:141], v[32:35], off offset:64 sc1
	global_store_dwordx4 v[140:141], v[4:7], off offset:512 sc1
	global_store_dwordx4 v[140:141], v[0:3], off offset:576 sc1
	s_mov_b32 s25, s23
	s_mov_b32 s24, s22
	s_andn2_b64 vcc, exec, s[10:11]
	s_cbranch_vccz .LBB0_2038

.LBB0_2103:
	s_or_b64 exec, exec, s[6:7]
	s_waitcnt vmcnt(11)
	v_mov_b32_e32 v52, v45
	s_waitcnt vmcnt(10)
	v_mov_b32_e32 v53, v41
	v_mov_b32_e32 v50, v44
	v_mov_b32_e32 v51, v40
	v_pk_mul_f32 v[52:53], v[52:53], v[52:53]
	s_waitcnt vmcnt(9)
	v_mov_b32_e32 v58, v37
	v_pk_fma_f32 v[50:51], v[50:51], v[50:51], v[52:53]
	v_mov_b32_e32 v52, v46
	v_mov_b32_e32 v53, v42
	v_pk_fma_f32 v[50:51], v[52:53], v[52:53], v[50:51]
	v_mov_b32_e32 v52, v47
	v_mov_b32_e32 v53, v43
	v_pk_fma_f32 v[50:51], v[52:53], v[52:53], v[50:51]
	global_load_dwordx4 v[208:211], v[66:67], off
	global_load_dwordx4 v[212:215], v[66:67], off offset:1024
	global_load_dwordx4 v[216:219], v[66:67], off offset:2048
	global_load_dwordx4 v[220:223], v[66:67], off offset:3072
	s_waitcnt vmcnt(12)
	v_mov_b32_e32 v59, v33
	v_mov_b32_e32 v56, v36
	v_mov_b32_e32 v57, v32
	v_pk_mul_f32 v[58:59], v[58:59], v[58:59]
	v_add_f32_e32 v50, v50, v51
	v_pk_fma_f32 v[56:57], v[56:57], v[56:57], v[58:59]
	v_mov_b32_e32 v58, v38
	v_mov_b32_e32 v59, v34
	v_pk_fma_f32 v[56:57], v[58:59], v[58:59], v[56:57]
	v_mov_b32_e32 v58, v39
	v_mov_b32_e32 v59, v35
	v_pk_fma_f32 v[56:57], v[58:59], v[58:59], v[56:57]
	s_waitcnt vmcnt(10)
	v_mov_b32_e32 v51, v24
	v_add_f32_e32 v50, v50, v56
	v_add_f32_e32 v61, v50, v57
	v_mov_b32_e32 v56, v29
	v_mov_b32_e32 v57, v25
	v_mov_b32_e32 v50, v28
	v_pk_mul_f32 v[56:57], v[56:57], v[56:57]
	s_waitcnt vmcnt(9)
	v_mov_b32_e32 v58, v21
	v_pk_fma_f32 v[50:51], v[50:51], v[50:51], v[56:57]
	v_mov_b32_e32 v56, v30
	v_mov_b32_e32 v57, v26
	v_pk_fma_f32 v[50:51], v[56:57], v[56:57], v[50:51]
	v_mov_b32_e32 v56, v31
	v_mov_b32_e32 v57, v27
	s_waitcnt vmcnt(8)
	v_mov_b32_e32 v59, v17
	v_pk_fma_f32 v[50:51], v[56:57], v[56:57], v[50:51]
	v_mov_b32_e32 v56, v20
	v_mov_b32_e32 v57, v16
	v_pk_mul_f32 v[58:59], v[58:59], v[58:59]
	v_add_f32_e32 v50, v50, v51
	v_pk_fma_f32 v[56:57], v[56:57], v[56:57], v[58:59]
	v_mov_b32_e32 v58, v22
	v_mov_b32_e32 v59, v18
	v_pk_fma_f32 v[56:57], v[58:59], v[58:59], v[56:57]
	v_mov_b32_e32 v58, v23
	v_mov_b32_e32 v59, v19
	v_pk_fma_f32 v[56:57], v[58:59], v[58:59], v[56:57]
	v_add_f32_dpp v51, v61, v61 quad_perm:[1,0,3,2] row_mask:0xf bank_mask:0xf bound_ctrl:1
	v_add_f32_e32 v50, v50, v56
	v_add_f32_e32 v50, v50, v57
	v_add_f32_dpp v51, v51, v51 quad_perm:[2,3,0,1] row_mask:0xf bank_mask:0xf bound_ctrl:1
	v_mov_b64_e32 v[84:85], s[4:5]
	v_add_f32_dpp v50, v50, v50 quad_perm:[1,0,3,2] row_mask:0xf bank_mask:0xf bound_ctrl:1
	v_add_f32_dpp v51, v51, v51 row_half_mirror row_mask:0xf bank_mask:0xf bound_ctrl:1
	v_lshl_add_u64 v[90:91], v[48:49], 0, v[62:63]
	v_add_f32_dpp v50, v50, v50 quad_perm:[2,3,0,1] row_mask:0xf bank_mask:0xf bound_ctrl:1
	v_add_f32_dpp v51, v51, v51 row_mirror row_mask:0xf bank_mask:0xf bound_ctrl:1
	s_nop 0
	v_add_f32_dpp v50, v50, v50 row_half_mirror row_mask:0xf bank_mask:0xf bound_ctrl:1
	v_readlane_b32 s9, v51, 16
	v_readlane_b32 s12, v51, 48
	v_add_f32_dpp v50, v50, v50 row_mirror row_mask:0xf bank_mask:0xf bound_ctrl:1
	v_readlane_b32 s6, v51, 0
	v_readlane_b32 s13, v50, 16
	v_readlane_b32 s14, v50, 48
	v_readlane_b32 s7, v51, 32
	v_readlane_b32 s10, v50, 0
	v_readlane_b32 s11, v50, 32
	v_mov_b32_e32 v50, s9
	v_mov_b32_e32 v51, s12
	v_mov_b32_e32 v56, s13
	v_mov_b32_e32 v57, s14
	v_pk_add_f32 v[50:51], s[6:7], v[50:51]
	v_pk_add_f32 v[56:57], s[10:11], v[56:57]
	v_mov_b32_e32 v59, v50
	v_mov_b32_e32 v58, v56
	v_mov_b32_e32 v50, v57
	v_pk_add_f32 v[50:51], v[58:59], v[50:51]
	s_nop 0
	v_pk_fma_f32 v[86:87], v[50:51], s[2:3], v[84:85] op_sel_hi:[1,0,0]
	s_nop 0
	v_mul_f32_e32 v50, 0x4b800000, v87
	v_cmp_gt_f32_e32 vcc, s8, v87
	s_nop 1
	v_cndmask_b32_e32 v50, v87, v50, vcc
	v_rsq_f32_e32 v50, v50
	s_nop 0
	v_mul_f32_e32 v51, 0x45800000, v50
	v_cndmask_b32_e32 v88, v50, v51, vcc
	v_pk_mul_f32 v[44:45], v[44:45], v[88:89] op_sel_hi:[1,0]
	v_pk_mul_f32 v[46:47], v[46:47], v[88:89] op_sel_hi:[1,0]
	s_waitcnt vmcnt(3)
	v_pk_mul_f32 v[80:81], v[44:45], v[208:209]
	v_pk_mul_f32 v[82:83], v[46:47], v[210:211]
	global_load_dwordx4 v[56:59], v[90:91], off
	global_load_dwordx4 v[52:55], v[90:91], off offset:1024
	global_load_dwordx4 v[48:51], v[90:91], off offset:2048
	global_load_dwordx4 v[44:47], v[90:91], off offset:3072
	v_pk_mul_f32 v[42:43], v[42:43], v[88:89] op_sel_hi:[1,0]
	global_store_dwordx4 v[74:75], v[80:83], off
	v_pk_mul_f32 v[40:41], v[40:41], v[88:89] op_sel_hi:[1,0]
	v_pk_mul_f32 v[38:39], v[38:39], v[88:89] op_sel_hi:[1,0]
	v_pk_mul_f32 v[36:37], v[36:37], v[88:89] op_sel_hi:[1,0]
	v_pk_mul_f32 v[34:35], v[34:35], v[88:89] op_sel_hi:[1,0]
	v_pk_mul_f32 v[32:33], v[32:33], v[88:89] op_sel_hi:[1,0]
	v_cmp_gt_f32_e32 vcc, s8, v86
	s_waitcnt vmcnt(0)
	v_pk_mul_f32 v[40:41], v[40:41], v[212:213]
	v_pk_mul_f32 v[42:43], v[42:43], v[214:215]
	global_store_dwordx4 v[74:75], v[40:43], off offset:1024
	v_pk_mul_f32 v[36:37], v[36:37], v[216:217]
	v_pk_mul_f32 v[38:39], v[38:39], v[218:219]
	global_store_dwordx4 v[74:75], v[36:39], off offset:2048
	v_mov_b32_e32 v40, v6
	v_mov_b32_e32 v41, v2
	v_pk_mul_f32 v[32:33], v[32:33], v[220:221]
	v_pk_mul_f32 v[34:35], v[34:35], v[222:223]
	global_store_dwordx4 v[74:75], v[32:35], off offset:3072
	v_mul_f32_e32 v36, 0x4b800000, v86
	v_cndmask_b32_e32 v36, v86, v36, vcc
	v_rsq_f32_e32 v38, v36
	v_lshlrev_b64 v[36:37], 12, v[72:73]
	v_lshl_add_u64 v[36:37], v[64:65], 0, v[36:37]
	v_mul_f32_e32 v39, 0x45800000, v38
	v_cndmask_b32_e32 v38, v38, v39, vcc
	v_pk_mul_f32 v[30:31], v[30:31], v[38:39] op_sel_hi:[1,0]
	v_pk_mul_f32 v[28:29], v[28:29], v[38:39] op_sel_hi:[1,0]
	v_pk_mul_f32 v[26:27], v[26:27], v[38:39] op_sel_hi:[1,0]
	v_pk_mul_f32 v[24:25], v[24:25], v[38:39] op_sel_hi:[1,0]
	v_pk_mul_f32 v[22:23], v[22:23], v[38:39] op_sel_hi:[1,0]
	v_pk_mul_f32 v[20:21], v[20:21], v[38:39] op_sel_hi:[1,0]
	v_pk_mul_f32 v[18:19], v[18:19], v[38:39] op_sel_hi:[1,0]
	v_pk_mul_f32 v[16:17], v[16:17], v[38:39] op_sel_hi:[1,0]
	v_mov_b32_e32 v38, v51
	v_mov_b32_e32 v39, v47
	v_pk_mul_f32 v[28:29], v[28:29], v[208:209]
	v_pk_mul_f32 v[30:31], v[30:31], v[210:211]
	global_store_dwordx4 v[36:37], v[28:31], off
	v_mov_b32_e32 v34, v5
	v_mov_b32_e32 v35, v1
	v_mov_b32_e32 v32, v4
	v_mov_b32_e32 v33, v0
	v_pk_mul_f32 v[24:25], v[24:25], v[212:213]
	v_pk_mul_f32 v[26:27], v[26:27], v[214:215]
	global_store_dwordx4 v[36:37], v[24:27], off offset:1024
	v_mov_b32_e32 v28, v14
	v_mov_b32_e32 v29, v10
	v_mov_b32_e32 v30, v15
	v_mov_b32_e32 v31, v11
	v_pk_mul_f32 v[20:21], v[20:21], v[216:217]
	v_pk_mul_f32 v[22:23], v[22:23], v[218:219]
	global_store_dwordx4 v[36:37], v[20:23], off offset:2048
	v_mov_b32_e32 v26, v13
	v_mov_b32_e32 v27, v9
	v_mov_b32_e32 v24, v12
	v_mov_b32_e32 v25, v8
	v_pk_mul_f32 v[16:17], v[16:17], v[220:221]
	v_pk_mul_f32 v[18:19], v[18:19], v[222:223]
	global_store_dwordx4 v[36:37], v[16:19], off offset:3072
	v_pk_mul_f32 v[22:23], v[26:27], v[26:27]
	v_pk_mul_f32 v[26:27], v[34:35], v[34:35]
	v_pk_fma_f32 v[22:23], v[24:25], v[24:25], v[22:23]
	v_pk_fma_f32 v[24:25], v[32:33], v[32:33], v[26:27]
	v_pk_fma_f32 v[22:23], v[28:29], v[28:29], v[22:23]
	v_mov_b32_e32 v20, v7
	v_mov_b32_e32 v21, v3
	v_pk_fma_f32 v[24:25], v[40:41], v[40:41], v[24:25]
	v_pk_fma_f32 v[22:23], v[30:31], v[30:31], v[22:23]
	v_pk_fma_f32 v[20:21], v[20:21], v[20:21], v[24:25]
	v_add_f32_e32 v22, v22, v23
	v_add_f32_e32 v20, v22, v20
	v_add_f32_e32 v20, v20, v21
	v_mov_b32_e32 v26, v57
	v_mov_b32_e32 v27, v53
	v_add_f32_dpp v20, v20, v20 quad_perm:[1,0,3,2] row_mask:0xf bank_mask:0xf bound_ctrl:1
	v_mov_b32_e32 v24, v56
	v_mov_b32_e32 v25, v52
	v_add_f32_dpp v20, v20, v20 quad_perm:[2,3,0,1] row_mask:0xf bank_mask:0xf bound_ctrl:1
	v_mov_b32_e32 v34, v49
	v_mov_b32_e32 v35, v45
	v_add_f32_dpp v20, v20, v20 row_half_mirror row_mask:0xf bank_mask:0xf bound_ctrl:1
	v_pk_mul_f32 v[26:27], v[26:27], v[26:27]
	v_mov_b32_e32 v28, v58
	v_add_f32_dpp v20, v20, v20 row_mirror row_mask:0xf bank_mask:0xf bound_ctrl:1
	v_mov_b32_e32 v29, v54
	v_readlane_b32 s9, v20, 16
	v_readlane_b32 s10, v20, 48
	v_mov_b32_e32 v32, v48
	v_mov_b32_e32 v33, v44
	v_pk_mul_f32 v[34:35], v[34:35], v[34:35]
	v_pk_fma_f32 v[24:25], v[24:25], v[24:25], v[26:27]
	v_readlane_b32 s6, v20, 0
	v_readlane_b32 s7, v20, 32
	v_mov_b32_e32 v20, s9
	v_mov_b32_e32 v21, s10
	v_mov_b32_e32 v30, v59
	v_mov_b32_e32 v31, v55
	v_mov_b32_e32 v36, v50
	v_mov_b32_e32 v37, v46
	v_pk_fma_f32 v[26:27], v[32:33], v[32:33], v[34:35]
	v_pk_fma_f32 v[24:25], v[28:29], v[28:29], v[24:25]
	v_pk_add_f32 v[20:21], s[6:7], v[20:21]
	v_pk_fma_f32 v[26:27], v[36:37], v[36:37], v[26:27]
	v_pk_fma_f32 v[24:25], v[30:31], v[30:31], v[24:25]
	v_mov_b32_e32 v23, v20
	v_pk_fma_f32 v[26:27], v[38:39], v[38:39], v[26:27]
	v_add_f32_e32 v20, v24, v25
	v_add_f32_e32 v20, v20, v26
	v_add_f32_e32 v20, v20, v27
	s_nop 1
	v_add_f32_dpp v20, v20, v20 quad_perm:[1,0,3,2] row_mask:0xf bank_mask:0xf bound_ctrl:1
	s_nop 1
	v_add_f32_dpp v20, v20, v20 quad_perm:[2,3,0,1] row_mask:0xf bank_mask:0xf bound_ctrl:1
	s_nop 1
	v_add_f32_dpp v20, v20, v20 row_half_mirror row_mask:0xf bank_mask:0xf bound_ctrl:1
	s_nop 1
	v_add_f32_dpp v20, v20, v20 row_mirror row_mask:0xf bank_mask:0xf bound_ctrl:1
	s_nop 0
	v_readlane_b32 s9, v20, 16
	v_readlane_b32 s10, v20, 48
	v_readlane_b32 s6, v20, 0
	v_readlane_b32 s7, v20, 32
	v_mov_b32_e32 v24, s9
	v_mov_b32_e32 v25, s10
	v_pk_add_f32 v[24:25], s[6:7], v[24:25]
	s_mov_b32 s6, s20
	v_mov_b32_e32 v22, v24
	v_mov_b32_e32 v20, v25
	v_pk_add_f32 v[20:21], v[22:23], v[20:21]
	s_nop 0
	v_pk_fma_f32 v[20:21], v[20:21], s[2:3], v[84:85] op_sel_hi:[1,0,0]
	s_nop 0
	v_mul_f32_e32 v22, 0x4b800000, v21
	v_cmp_gt_f32_e32 vcc, s8, v21
	s_nop 1
	v_cndmask_b32_e32 v21, v21, v22, vcc
	v_rsq_f32_e32 v21, v21
	v_lshlrev_b64 v[22:23], 12, v[70:71]
	v_lshl_add_u64 v[22:23], v[64:65], 0, v[22:23]
	v_mul_f32_e32 v24, 0x45800000, v21
	v_cndmask_b32_e32 v24, v21, v24, vcc
	v_pk_mul_f32 v[14:15], v[14:15], v[24:25] op_sel_hi:[1,0]
	v_pk_mul_f32 v[12:13], v[12:13], v[24:25] op_sel_hi:[1,0]
	v_pk_mul_f32 v[14:15], v[14:15], v[210:211]
	v_pk_mul_f32 v[12:13], v[12:13], v[208:209]
	global_store_dwordx4 v[22:23], v[12:15], off
	v_pk_mul_f32 v[10:11], v[10:11], v[24:25] op_sel_hi:[1,0]
	v_pk_mul_f32 v[8:9], v[8:9], v[24:25] op_sel_hi:[1,0]
	v_pk_mul_f32 v[6:7], v[6:7], v[24:25] op_sel_hi:[1,0]
	v_pk_mul_f32 v[4:5], v[4:5], v[24:25] op_sel_hi:[1,0]
	v_pk_mul_f32 v[2:3], v[2:3], v[24:25] op_sel_hi:[1,0]
	v_pk_mul_f32 v[0:1], v[0:1], v[24:25] op_sel_hi:[1,0]
	v_cmp_gt_f32_e32 vcc, s8, v20
	v_pk_mul_f32 v[8:9], v[8:9], v[212:213]
	v_pk_mul_f32 v[10:11], v[10:11], v[214:215]
	global_store_dwordx4 v[22:23], v[8:11], off offset:1024
	v_pk_mul_f32 v[4:5], v[4:5], v[216:217]
	v_pk_mul_f32 v[6:7], v[6:7], v[218:219]
	global_store_dwordx4 v[22:23], v[4:7], off offset:2048
	v_pk_mul_f32 v[0:1], v[0:1], v[220:221]
	v_pk_mul_f32 v[2:3], v[2:3], v[222:223]
	global_store_dwordx4 v[22:23], v[0:3], off offset:3072
	v_mul_f32_e32 v4, 0x4b800000, v20
	v_cndmask_b32_e32 v4, v20, v4, vcc
	v_rsq_f32_e32 v6, v4
	v_lshl_add_u64 v[4:5], v[64:65], 0, v[68:69]
	v_mul_f32_e32 v7, 0x45800000, v6
	v_cndmask_b32_e32 v6, v6, v7, vcc
	v_pk_mul_f32 v[8:9], v[58:59], v[6:7] op_sel_hi:[1,0]
	v_pk_mul_f32 v[10:11], v[56:57], v[6:7] op_sel_hi:[1,0]
	v_pk_mul_f32 v[2:3], v[8:9], v[210:211]
	v_pk_mul_f32 v[0:1], v[10:11], v[208:209]
	global_store_dwordx4 v[4:5], v[0:3], off
	v_pk_mul_f32 v[8:9], v[54:55], v[6:7] op_sel_hi:[1,0]
	v_pk_mul_f32 v[10:11], v[52:53], v[6:7] op_sel_hi:[1,0]
	v_pk_mul_f32 v[2:3], v[8:9], v[214:215]
	v_pk_mul_f32 v[0:1], v[10:11], v[212:213]
	global_store_dwordx4 v[4:5], v[0:3], off offset:1024
	v_pk_mul_f32 v[8:9], v[50:51], v[6:7] op_sel_hi:[1,0]
	v_pk_mul_f32 v[10:11], v[48:49], v[6:7] op_sel_hi:[1,0]
	v_pk_mul_f32 v[2:3], v[8:9], v[218:219]
	v_pk_mul_f32 v[0:1], v[10:11], v[216:217]
	global_store_dwordx4 v[4:5], v[0:3], off offset:2048
	v_pk_mul_f32 v[8:9], v[46:47], v[6:7] op_sel_hi:[1,0]
	v_pk_mul_f32 v[6:7], v[44:45], v[6:7] op_sel_hi:[1,0]
	v_pk_mul_f32 v[2:3], v[8:9], v[222:223]
	v_pk_mul_f32 v[0:1], v[6:7], v[220:221]
	global_store_dwordx4 v[4:5], v[0:3], off offset:3072
	s_nop 0
	v_lshl_add_u32 v60, s6, 4, v60
	v_cmp_lt_i32_e32 vcc, s5, v60
	s_or_b64 s[0:1], vcc, s[0:1]
	s_andn2_b64 exec, exec, s[0:1]
	s_cbranch_execz .LBB0_2108
